# merged dual-GEMM output stores nontemporal as well
# baseline (speedup 1.0000x reference)
; template <class T> DI T gld_nt(const void* base, unsigned off) { return __builtin_nontemporal_load((const T*)((const char*)base + off)); }
; DI u32x4 pk8(const f32x4& a, const f32x4& b) { u32x4 w; w.x = pk2(a[0], a[1]); w.y = pk2(a[2], a[3]); w.z = pk2(b[0], b[1]); w.w = pk2(b[2], b[3]); return w; }
; DI void unpk8(const u32x4& w, f32x4& a, f32x4& b) { a[0] = bf_lo(w.x); a[1] = bf_hi(w.x); a[2] = bf_lo(w.y); a[3] = bf_hi(w.y); b[0] = bf_lo(w.z); b[1] = bf_hi(w.z); b[2] = bf_lo(w.w); b[3] = bf_hi(w.w); }
; template <bool NT = false> DI void st_rows16(void* base, unsigned pitch_b, unsigned row0, unsigned col0, int fr, int fq, const u32x4& w0, const u32x4& w1) {
;   u32x4 x;
; #pragma unroll
;   for (int e = 0; e < 4; ++e) x[e] = (unsigned)__builtin_amdgcn_update_dpp(0, (int)w1[e], 0x128  , 0xf, 0xf, false);
;   const bool hi = fr >= 8;
;   u32x4 pa, pb;
; #pragma unroll
;   for (int e = 0; e < 4; ++e) { pa[e] = hi ? x[e] : w0[e]; pb[e] = hi ? w0[e] : x[e]; }
;   const unsigned ra = row0 + (unsigned)(fr & 7), ca = col0 + 8u * fq + (hi ? 32u : 0u), cb = col0 + 8u * fq + (hi ? 0u : 32u);
;   if (NT) { __builtin_nontemporal_store(pa, (u32x4*)((char*)base + (ra * pitch_b + ca * 2u))); __builtin_nontemporal_store(pb, (u32x4*)((char*)base + ((ra + 8u) * pitch_b + cb * 2u))); }
;   else { gst<u32x4>(base, ra * pitch_b + ca * 2u, pa); gst<u32x4>(base, (ra + 8u) * pitch_b + cb * 2u, pb); }
; }
;   DI void operator()(g8::Acc& acc, int pm, int pn, int wr, int wc, int fr, int fq) const {
;     using namespace g8;
; #pragma unroll
;     for (int ai = 0; ai < 2; ++ai)
; #pragma unroll
;       for (int m = 0; m < 4; ++m) {
;         const int row0 = pm * BM + ai * HALF + wr * 64 + m * 16, row = row0 + fr; u32x4 wv[2];
; #pragma unroll
;         for (int bj = 0; bj < 2; ++bj) {
;           const int col8 = pn * BM + wc * 64 + bj * 32 + fq * 8; const unsigned go = ((unsigned)row * 2048u + (unsigned)(1024 + col8)) * 2u;
;           f32x4 s0, s1; unpk8(gld_nt<u32x4>(gates, go), s0, s1);
; #pragma unroll
;           for (int e = 0; e < 4; ++e) { s0[e] = fmaxf(s0[e], 1e-30f); s1[e] = fmaxf(s1[e], 1e-30f); }
;           wv[bj] = pk8(acc[ai][bj][m][0] * s0, acc[ai][bj][m][1] * s1);
;         }
;         st_rows16(dst, DM * 2u, (unsigned)row0, (unsigned)(pn * BM + wc * 64), fr, fq, wv[0], wv[1]);
;       }
;   }
.LBB0_485:
	s_and_b64 vcc, exec, s[52:53]
	s_cbranch_vccz .LBB0_493
	s_lshl_b32 s0, s58, 8
	s_add_i32 s0, s0, s15
	v_lshl_add_u32 v153, s33, 9, v143
	v_or_b32_e32 v151, s0, v140
	v_lshl_add_u32 v151, v151, 12, v153
	global_load_dwordx4 v[154:157], v151, s[72:73] nt
	global_load_dwordx4 v[158:161], v151, s[72:73] offset:64 nt
	v_lshl_or_b32 v151, s33, 8, v145
	v_mov_b32_e32 v170, 0
	v_mov_b32_e32 v171, 0
	v_mov_b32_e32 v172, 0
	v_mov_b32_e32 v173, 0
	v_or_b32_e32 v152, v151, v146
	v_or_b32_e32 v151, v151, v147
	v_lshlrev_b32_e32 v152, 1, v152
	v_lshl_add_u32 v151, v151, 1, v150
	s_or_b32 s1, s0, 16
	s_waitcnt vmcnt(0)
	v_lshlrev_b32_e32 v162, 16, v154
	v_and_b32_e32 v154, 0xffff0000, v154
	v_lshlrev_b32_e32 v163, 16, v155
	v_and_b32_e32 v155, 0xffff0000, v155
	v_lshlrev_b32_e32 v164, 16, v156
	v_and_b32_e32 v156, 0xffff0000, v156
	v_lshlrev_b32_e32 v165, 16, v157
	v_and_b32_e32 v157, 0xffff0000, v157
	v_lshlrev_b32_e32 v166, 16, v158
	v_and_b32_e32 v158, 0xffff0000, v158
	v_lshlrev_b32_e32 v167, 16, v159
	v_and_b32_e32 v159, 0xffff0000, v159
	v_lshlrev_b32_e32 v168, 16, v160
	v_and_b32_e32 v160, 0xffff0000, v160
	v_lshlrev_b32_e32 v169, 16, v161
	v_and_b32_e32 v161, 0xffff0000, v161
	v_max_f32_e32 v162, v162, v162
	v_max_f32_e32 v164, v164, v164
	v_max_f32_e32 v174, v154, v154
	v_max_f32_e32 v175, v156, v156
	v_max_f32_e32 v163, v163, v163
	v_max_f32_e32 v165, v165, v165
	v_max_f32_e32 v176, v155, v155
	v_max_f32_e32 v177, v157, v157
	v_max_f32_e32 v166, v166, v166
	v_max_f32_e32 v168, v168, v168
	v_max_f32_e32 v178, v158, v158
	v_max_f32_e32 v179, v160, v160
	v_max_f32_e32 v167, v167, v167
	v_max_f32_e32 v169, v169, v169
	v_max_f32_e32 v180, v159, v159
	v_max_f32_e32 v181, v161, v161
	v_max_f32_e32 v154, 0xda24260, v162
	v_max_f32_e32 v156, 0xda24260, v164
	v_max_f32_e32 v155, 0xda24260, v174
	v_max_f32_e32 v157, 0xda24260, v175
	v_max_f32_e32 v158, 0xda24260, v163
	v_max_f32_e32 v160, 0xda24260, v165
	v_max_f32_e32 v159, 0xda24260, v176
	v_max_f32_e32 v161, 0xda24260, v177
	v_max_f32_e32 v162, 0xda24260, v166
	v_max_f32_e32 v164, 0xda24260, v168
	v_max_f32_e32 v163, 0xda24260, v178
	v_max_f32_e32 v165, 0xda24260, v179
	v_max_f32_e32 v166, 0xda24260, v167
	v_max_f32_e32 v168, 0xda24260, v169
	v_max_f32_e32 v167, 0xda24260, v180
	v_max_f32_e32 v169, 0xda24260, v181
	v_pk_mul_f32 v[158:159], v[126:127], v[158:159]
	v_pk_mul_f32 v[154:155], v[124:125], v[154:155]
	v_pk_mul_f32 v[160:161], v[122:123], v[160:161]
	v_pk_mul_f32 v[156:157], v[120:121], v[156:157]
	v_pk_mul_f32 v[166:167], v[94:95], v[166:167]
	v_pk_mul_f32 v[162:163], v[92:93], v[162:163]
	v_pk_mul_f32 v[168:169], v[90:91], v[168:169]
	v_pk_mul_f32 v[164:165], v[88:89], v[164:165]
	v_cvt_pk_bf16_f32 v155, v154, v155
	v_cvt_pk_bf16_f32 v159, v158, v159
	v_cvt_pk_bf16_f32 v157, v156, v157
	v_cvt_pk_bf16_f32 v161, v160, v161
	v_cvt_pk_bf16_f32 v154, v162, v163
	v_cvt_pk_bf16_f32 v156, v166, v167
	v_cvt_pk_bf16_f32 v158, v164, v165
	v_cvt_pk_bf16_f32 v160, v168, v169
	v_or_b32_e32 v162, s0, v144
	v_mov_b32_dpp v170, v154 row_ror:8 row_mask:0xf bank_mask:0xf
	v_mov_b32_dpp v171, v156 row_ror:8 row_mask:0xf bank_mask:0xf
	v_mov_b32_dpp v172, v158 row_ror:8 row_mask:0xf bank_mask:0xf
	v_mov_b32_dpp v173, v160 row_ror:8 row_mask:0xf bank_mask:0xf
	v_lshlrev_b32_e32 v162, 11, v162
	v_cndmask_b32_e64 v154, v155, v170, s[4:5]
	v_cndmask_b32_e64 v158, v170, v155, s[4:5]
	v_cndmask_b32_e64 v155, v159, v171, s[4:5]
	v_cndmask_b32_e64 v156, v157, v172, s[4:5]
	v_cndmask_b32_e64 v160, v172, v157, s[4:5]
	v_cndmask_b32_e64 v157, v161, v173, s[4:5]
	v_add_u32_e32 v163, v152, v162
	v_cndmask_b32_e64 v159, v171, v159, s[4:5]
	v_cndmask_b32_e64 v161, v173, v161, s[4:5]
	global_store_dwordx4 v163, v[154:157], s[12:13] nt
	v_mov_b32_e32 v170, 0
	v_mov_b32_e32 v171, 0
	v_add_u32_e32 v154, v151, v162
	global_store_dwordx4 v154, v[158:161], s[12:13] nt
	v_or_b32_e32 v154, s1, v140
	v_mov_b32_e32 v172, 0
	v_lshl_add_u32 v158, v154, 12, v153
	global_load_dwordx4 v[154:157], v158, s[72:73] nt
	s_nop 0
	global_load_dwordx4 v[158:161], v158, s[72:73] offset:64 nt
	v_mov_b32_e32 v173, 0
	s_waitcnt vmcnt(1)
	v_lshlrev_b32_e32 v162, 16, v154
	v_and_b32_e32 v154, 0xffff0000, v154
	v_lshlrev_b32_e32 v163, 16, v155
	v_and_b32_e32 v155, 0xffff0000, v155
	v_lshlrev_b32_e32 v164, 16, v156
	v_and_b32_e32 v156, 0xffff0000, v156
	v_lshlrev_b32_e32 v165, 16, v157
	v_and_b32_e32 v157, 0xffff0000, v157
	s_waitcnt vmcnt(0)
; template <class T> DI T gld_nt(const void* base, unsigned off) { return __builtin_nontemporal_load((const T*)((const char*)base + off)); }
; DI u32x4 pk8(const f32x4& a, const f32x4& b) { u32x4 w; w.x = pk2(a[0], a[1]); w.y = pk2(a[2], a[3]); w.z = pk2(b[0], b[1]); w.w = pk2(b[2], b[3]); return w; }
; DI void unpk8(const u32x4& w, f32x4& a, f32x4& b) { a[0] = bf_lo(w.x); a[1] = bf_hi(w.x); a[2] = bf_lo(w.y); a[3] = bf_hi(w.y); b[0] = bf_lo(w.z); b[1] = bf_hi(w.z); b[2] = bf_lo(w.w); b[3] = bf_hi(w.w); }
; template <bool NT = false> DI void st_rows16(void* base, unsigned pitch_b, unsigned row0, unsigned col0, int fr, int fq, const u32x4& w0, const u32x4& w1) {
;   u32x4 x;
; #pragma unroll
;   for (int e = 0; e < 4; ++e) x[e] = (unsigned)__builtin_amdgcn_update_dpp(0, (int)w1[e], 0x128  , 0xf, 0xf, false);
;   const bool hi = fr >= 8;
;   u32x4 pa, pb;
; #pragma unroll
;   for (int e = 0; e < 4; ++e) { pa[e] = hi ? x[e] : w0[e]; pb[e] = hi ? w0[e] : x[e]; }
;   const unsigned ra = row0 + (unsigned)(fr & 7), ca = col0 + 8u * fq + (hi ? 32u : 0u), cb = col0 + 8u * fq + (hi ? 0u : 32u);
;   if (NT) { __builtin_nontemporal_store(pa, (u32x4*)((char*)base + (ra * pitch_b + ca * 2u))); __builtin_nontemporal_store(pb, (u32x4*)((char*)base + ((ra + 8u) * pitch_b + cb * 2u))); }
;   else { gst<u32x4>(base, ra * pitch_b + ca * 2u, pa); gst<u32x4>(base, (ra + 8u) * pitch_b + cb * 2u, pb); }
; }
;   DI void operator()(g8::Acc& acc, int pm, int pn, int wr, int wc, int fr, int fq) const {
;     using namespace g8;
; #pragma unroll
;     for (int ai = 0; ai < 2; ++ai)
; #pragma unroll
;       for (int m = 0; m < 4; ++m) {
;         const int row0 = pm * BM + ai * HALF + wr * 64 + m * 16, row = row0 + fr; u32x4 wv[2];
; #pragma unroll
;         for (int bj = 0; bj < 2; ++bj) {
;           const int col8 = pn * BM + wc * 64 + bj * 32 + fq * 8; const unsigned go = ((unsigned)row * 2048u + (unsigned)(1024 + col8)) * 2u;
;           f32x4 s0, s1; unpk8(gld_nt<u32x4>(gates, go), s0, s1);
; #pragma unroll
;           for (int e = 0; e < 4; ++e) { s0[e] = fmaxf(s0[e], 1e-30f); s1[e] = fmaxf(s1[e], 1e-30f); }
;           wv[bj] = pk8(acc[ai][bj][m][0] * s0, acc[ai][bj][m][1] * s1);
;         }
;         st_rows16(dst, DM * 2u, (unsigned)row0, (unsigned)(pn * BM + wc * 64), fr, fq, wv[0], wv[1]);
;       }
;   }
	v_lshlrev_b32_e32 v166, 16, v158
	v_and_b32_e32 v158, 0xffff0000, v158
	v_lshlrev_b32_e32 v167, 16, v159
	v_and_b32_e32 v159, 0xffff0000, v159
	v_lshlrev_b32_e32 v168, 16, v160
	v_and_b32_e32 v160, 0xffff0000, v160
	v_lshlrev_b32_e32 v169, 16, v161
	v_and_b32_e32 v161, 0xffff0000, v161
	v_max_f32_e32 v162, v162, v162
	v_max_f32_e32 v164, v164, v164
	v_max_f32_e32 v174, v154, v154
	v_max_f32_e32 v175, v156, v156
	v_max_f32_e32 v163, v163, v163
	v_max_f32_e32 v165, v165, v165
	v_max_f32_e32 v176, v155, v155
	v_max_f32_e32 v177, v157, v157
	v_max_f32_e32 v166, v166, v166
	v_max_f32_e32 v168, v168, v168
	v_max_f32_e32 v178, v158, v158
	v_max_f32_e32 v179, v160, v160
	v_max_f32_e32 v167, v167, v167
	v_max_f32_e32 v169, v169, v169
	v_max_f32_e32 v180, v159, v159
	v_max_f32_e32 v181, v161, v161
	v_max_f32_e32 v154, 0xda24260, v162
	v_max_f32_e32 v156, 0xda24260, v164
	v_max_f32_e32 v155, 0xda24260, v174
	v_max_f32_e32 v157, 0xda24260, v175
	v_max_f32_e32 v158, 0xda24260, v163
	v_max_f32_e32 v160, 0xda24260, v165
	v_max_f32_e32 v159, 0xda24260, v176
	v_max_f32_e32 v161, 0xda24260, v177
	v_max_f32_e32 v162, 0xda24260, v166
	v_max_f32_e32 v164, 0xda24260, v168
	v_max_f32_e32 v163, 0xda24260, v178
	v_max_f32_e32 v165, 0xda24260, v179
	v_max_f32_e32 v166, 0xda24260, v167
	v_max_f32_e32 v168, 0xda24260, v169
	v_max_f32_e32 v167, 0xda24260, v180
	v_max_f32_e32 v169, 0xda24260, v181
	v_pk_mul_f32 v[158:159], v[118:119], v[158:159]
	v_pk_mul_f32 v[154:155], v[116:117], v[154:155]
	v_pk_mul_f32 v[160:161], v[114:115], v[160:161]
	v_pk_mul_f32 v[156:157], v[112:113], v[156:157]
	v_pk_mul_f32 v[166:167], v[86:87], v[166:167]
	v_pk_mul_f32 v[162:163], v[84:85], v[162:163]
	v_pk_mul_f32 v[168:169], v[82:83], v[168:169]
	v_pk_mul_f32 v[164:165], v[80:81], v[164:165]
	v_cvt_pk_bf16_f32 v155, v154, v155
	v_cvt_pk_bf16_f32 v159, v158, v159
	v_cvt_pk_bf16_f32 v157, v156, v157
	v_cvt_pk_bf16_f32 v161, v160, v161
	v_cvt_pk_bf16_f32 v154, v162, v163
	v_cvt_pk_bf16_f32 v156, v166, v167
	v_cvt_pk_bf16_f32 v158, v164, v165
	v_cvt_pk_bf16_f32 v160, v168, v169
	v_or_b32_e32 v162, s1, v144
	v_mov_b32_dpp v170, v154 row_ror:8 row_mask:0xf bank_mask:0xf
	v_mov_b32_dpp v171, v156 row_ror:8 row_mask:0xf bank_mask:0xf
	v_mov_b32_dpp v172, v158 row_ror:8 row_mask:0xf bank_mask:0xf
	v_mov_b32_dpp v173, v160 row_ror:8 row_mask:0xf bank_mask:0xf
	v_lshlrev_b32_e32 v162, 11, v162
	v_cndmask_b32_e64 v154, v155, v170, s[4:5]
	v_cndmask_b32_e64 v158, v170, v155, s[4:5]
	v_cndmask_b32_e64 v155, v159, v171, s[4:5]
	v_cndmask_b32_e64 v156, v157, v172, s[4:5]
	v_cndmask_b32_e64 v160, v172, v157, s[4:5]
	v_cndmask_b32_e64 v157, v161, v173, s[4:5]
	v_add_u32_e32 v163, v152, v162
	v_cndmask_b32_e64 v159, v171, v159, s[4:5]
	v_cndmask_b32_e64 v161, v173, v161, s[4:5]
	global_store_dwordx4 v163, v[154:157], s[12:13] nt
	s_or_b32 s1, s0, 32
	v_mov_b32_e32 v170, 0
	v_add_u32_e32 v154, v151, v162
	global_store_dwordx4 v154, v[158:161], s[12:13] nt
	v_or_b32_e32 v154, s1, v140
	v_mov_b32_e32 v171, 0
	v_lshl_add_u32 v158, v154, 12, v153
	global_load_dwordx4 v[154:157], v158, s[72:73] nt
	s_nop 0
	global_load_dwordx4 v[158:161], v158, s[72:73] offset:64 nt
	v_mov_b32_e32 v172, 0
	v_mov_b32_e32 v173, 0
	s_waitcnt vmcnt(1)
	v_lshlrev_b32_e32 v162, 16, v154
	v_and_b32_e32 v154, 0xffff0000, v154
	v_lshlrev_b32_e32 v163, 16, v155
	v_and_b32_e32 v155, 0xffff0000, v155
	v_lshlrev_b32_e32 v164, 16, v156
	v_and_b32_e32 v156, 0xffff0000, v156
	v_lshlrev_b32_e32 v165, 16, v157
	v_and_b32_e32 v157, 0xffff0000, v157
	s_waitcnt vmcnt(0)
	v_lshlrev_b32_e32 v166, 16, v158
	v_and_b32_e32 v158, 0xffff0000, v158
	v_lshlrev_b32_e32 v167, 16, v159
	v_and_b32_e32 v159, 0xffff0000, v159
	v_lshlrev_b32_e32 v168, 16, v160
	v_and_b32_e32 v160, 0xffff0000, v160
	v_lshlrev_b32_e32 v169, 16, v161
	v_and_b32_e32 v161, 0xffff0000, v161
	v_max_f32_e32 v162, v162, v162
	v_max_f32_e32 v164, v164, v164
	v_max_f32_e32 v174, v154, v154
	v_max_f32_e32 v175, v156, v156
	v_max_f32_e32 v163, v163, v163
	v_max_f32_e32 v165, v165, v165
	v_max_f32_e32 v176, v155, v155
	v_max_f32_e32 v177, v157, v157
	v_max_f32_e32 v166, v166, v166
	v_max_f32_e32 v168, v168, v168
	v_max_f32_e32 v178, v158, v158
	v_max_f32_e32 v179, v160, v160
	v_max_f32_e32 v167, v167, v167
	v_max_f32_e32 v169, v169, v169
	v_max_f32_e32 v180, v159, v159
	v_max_f32_e32 v181, v161, v161
	v_max_f32_e32 v154, 0xda24260, v162
	v_max_f32_e32 v156, 0xda24260, v164
	v_max_f32_e32 v155, 0xda24260, v174
	v_max_f32_e32 v157, 0xda24260, v175
	v_max_f32_e32 v158, 0xda24260, v163
	v_max_f32_e32 v160, 0xda24260, v165
	v_max_f32_e32 v159, 0xda24260, v176
	v_max_f32_e32 v161, 0xda24260, v177
	v_max_f32_e32 v162, 0xda24260, v166
	v_max_f32_e32 v164, 0xda24260, v168
	v_max_f32_e32 v163, 0xda24260, v178
	v_max_f32_e32 v165, 0xda24260, v179
	v_max_f32_e32 v166, 0xda24260, v167
	v_max_f32_e32 v168, 0xda24260, v169
	v_max_f32_e32 v167, 0xda24260, v180
	v_max_f32_e32 v169, 0xda24260, v181
	v_pk_mul_f32 v[158:159], v[110:111], v[158:159]
	v_pk_mul_f32 v[154:155], v[108:109], v[154:155]
	v_pk_mul_f32 v[160:161], v[106:107], v[160:161]
	v_pk_mul_f32 v[156:157], v[104:105], v[156:157]
	v_pk_mul_f32 v[166:167], v[78:79], v[166:167]
	v_pk_mul_f32 v[162:163], v[76:77], v[162:163]
	v_pk_mul_f32 v[168:169], v[74:75], v[168:169]
	v_pk_mul_f32 v[164:165], v[72:73], v[164:165]
	v_cvt_pk_bf16_f32 v155, v154, v155
	v_cvt_pk_bf16_f32 v159, v158, v159
	v_cvt_pk_bf16_f32 v157, v156, v157
	v_cvt_pk_bf16_f32 v161, v160, v161
	v_cvt_pk_bf16_f32 v154, v162, v163
	v_cvt_pk_bf16_f32 v156, v166, v167
	v_cvt_pk_bf16_f32 v158, v164, v165
	v_cvt_pk_bf16_f32 v160, v168, v169
	v_or_b32_e32 v162, s1, v144
	v_mov_b32_dpp v170, v154 row_ror:8 row_mask:0xf bank_mask:0xf
	v_mov_b32_dpp v171, v156 row_ror:8 row_mask:0xf bank_mask:0xf
	v_mov_b32_dpp v172, v158 row_ror:8 row_mask:0xf bank_mask:0xf
	v_mov_b32_dpp v173, v160 row_ror:8 row_mask:0xf bank_mask:0xf
	v_lshlrev_b32_e32 v162, 11, v162
	v_cndmask_b32_e64 v154, v155, v170, s[4:5]
	v_cndmask_b32_e64 v158, v170, v155, s[4:5]
	v_cndmask_b32_e64 v155, v159, v171, s[4:5]
	v_cndmask_b32_e64 v156, v157, v172, s[4:5]
	v_cndmask_b32_e64 v160, v172, v157, s[4:5]
	v_cndmask_b32_e64 v157, v161, v173, s[4:5]
	v_add_u32_e32 v163, v152, v162
	v_cndmask_b32_e64 v159, v171, v159, s[4:5]
	v_cndmask_b32_e64 v161, v173, v161, s[4:5]
	global_store_dwordx4 v163, v[154:157], s[12:13] nt
	s_or_b32 s1, s0, 48
	v_mov_b32_e32 v172, 0
	v_add_u32_e32 v154, v151, v162
	global_store_dwordx4 v154, v[158:161], s[12:13] nt
	v_or_b32_e32 v154, s1, v140
	v_mov_b32_e32 v171, 0
	v_lshl_add_u32 v158, v154, 12, v153
	global_load_dwordx4 v[154:157], v158, s[72:73] nt
	s_nop 0
	global_load_dwordx4 v[158:161], v158, s[72:73] offset:64 nt
	v_mov_b32_e32 v170, 0
	s_waitcnt vmcnt(1)
; template <class T> DI T gld_nt(const void* base, unsigned off) { return __builtin_nontemporal_load((const T*)((const char*)base + off)); }
; DI u32x4 pk8(const f32x4& a, const f32x4& b) { u32x4 w; w.x = pk2(a[0], a[1]); w.y = pk2(a[2], a[3]); w.z = pk2(b[0], b[1]); w.w = pk2(b[2], b[3]); return w; }
; DI void unpk8(const u32x4& w, f32x4& a, f32x4& b) { a[0] = bf_lo(w.x); a[1] = bf_hi(w.x); a[2] = bf_lo(w.y); a[3] = bf_hi(w.y); b[0] = bf_lo(w.z); b[1] = bf_hi(w.z); b[2] = bf_lo(w.w); b[3] = bf_hi(w.w); }
; template <bool NT = false> DI void st_rows16(void* base, unsigned pitch_b, unsigned row0, unsigned col0, int fr, int fq, const u32x4& w0, const u32x4& w1) {
;   u32x4 x;
; #pragma unroll
;   for (int e = 0; e < 4; ++e) x[e] = (unsigned)__builtin_amdgcn_update_dpp(0, (int)w1[e], 0x128  , 0xf, 0xf, false);
;   const bool hi = fr >= 8;
;   u32x4 pa, pb;
; #pragma unroll
;   for (int e = 0; e < 4; ++e) { pa[e] = hi ? x[e] : w0[e]; pb[e] = hi ? w0[e] : x[e]; }
;   const unsigned ra = row0 + (unsigned)(fr & 7), ca = col0 + 8u * fq + (hi ? 32u : 0u), cb = col0 + 8u * fq + (hi ? 0u : 32u);
;   if (NT) { __builtin_nontemporal_store(pa, (u32x4*)((char*)base + (ra * pitch_b + ca * 2u))); __builtin_nontemporal_store(pb, (u32x4*)((char*)base + ((ra + 8u) * pitch_b + cb * 2u))); }
;   else { gst<u32x4>(base, ra * pitch_b + ca * 2u, pa); gst<u32x4>(base, (ra + 8u) * pitch_b + cb * 2u, pb); }
; }
;   DI void operator()(g8::Acc& acc, int pm, int pn, int wr, int wc, int fr, int fq) const {
;     using namespace g8;
; #pragma unroll
;     for (int ai = 0; ai < 2; ++ai)
; #pragma unroll
;       for (int m = 0; m < 4; ++m) {
;         const int row0 = pm * BM + ai * HALF + wr * 64 + m * 16, row = row0 + fr; u32x4 wv[2];
; #pragma unroll
;         for (int bj = 0; bj < 2; ++bj) {
;           const int col8 = pn * BM + wc * 64 + bj * 32 + fq * 8; const unsigned go = ((unsigned)row * 2048u + (unsigned)(1024 + col8)) * 2u;
;           f32x4 s0, s1; unpk8(gld_nt<u32x4>(gates, go), s0, s1);
; #pragma unroll
;           for (int e = 0; e < 4; ++e) { s0[e] = fmaxf(s0[e], 1e-30f); s1[e] = fmaxf(s1[e], 1e-30f); }
;           wv[bj] = pk8(acc[ai][bj][m][0] * s0, acc[ai][bj][m][1] * s1);
;         }
;         st_rows16(dst, DM * 2u, (unsigned)row0, (unsigned)(pn * BM + wc * 64), fr, fq, wv[0], wv[1]);
;       }
;   }
	v_lshlrev_b32_e32 v162, 16, v154
	v_and_b32_e32 v154, 0xffff0000, v154
	v_lshlrev_b32_e32 v163, 16, v155
	v_and_b32_e32 v155, 0xffff0000, v155
	v_lshlrev_b32_e32 v164, 16, v156
	v_lshlrev_b32_e32 v165, 16, v157
	v_and_b32_e32 v157, 0xffff0000, v157
	s_waitcnt vmcnt(0)
	v_lshlrev_b32_e32 v166, 16, v158
	v_and_b32_e32 v158, 0xffff0000, v158
	v_lshlrev_b32_e32 v168, 16, v160
	v_and_b32_e32 v160, 0xffff0000, v160
	v_lshlrev_b32_e32 v169, 16, v161
	v_and_b32_e32 v161, 0xffff0000, v161
	v_and_b32_e32 v156, 0xffff0000, v156
	v_lshlrev_b32_e32 v167, 16, v159
	v_and_b32_e32 v159, 0xffff0000, v159
	v_max_f32_e32 v162, v162, v162
	v_max_f32_e32 v164, v164, v164
	v_max_f32_e32 v173, v154, v154
	v_max_f32_e32 v163, v163, v163
	v_max_f32_e32 v165, v165, v165
	v_max_f32_e32 v175, v155, v155
	v_max_f32_e32 v176, v157, v157
	v_max_f32_e32 v166, v166, v166
	v_max_f32_e32 v168, v168, v168
	v_max_f32_e32 v177, v158, v158
	v_max_f32_e32 v178, v160, v160
	v_max_f32_e32 v169, v169, v169
	v_max_f32_e32 v180, v161, v161
	v_max_f32_e32 v174, v156, v156
	v_max_f32_e32 v167, v167, v167
	v_max_f32_e32 v179, v159, v159
	v_max_f32_e32 v154, 0xda24260, v162
	v_max_f32_e32 v156, 0xda24260, v164
	v_max_f32_e32 v155, 0xda24260, v173
	v_max_f32_e32 v158, 0xda24260, v163
	v_max_f32_e32 v160, 0xda24260, v165
	v_max_f32_e32 v159, 0xda24260, v175
	v_max_f32_e32 v161, 0xda24260, v176
	v_max_f32_e32 v162, 0xda24260, v166
	v_max_f32_e32 v164, 0xda24260, v168
	v_max_f32_e32 v163, 0xda24260, v177
	v_max_f32_e32 v165, 0xda24260, v178
	v_max_f32_e32 v168, 0xda24260, v169
	v_max_f32_e32 v169, 0xda24260, v180
	v_max_f32_e32 v157, 0xda24260, v174
	v_max_f32_e32 v166, 0xda24260, v167
	v_max_f32_e32 v167, 0xda24260, v179
	v_pk_mul_f32 v[158:159], v[102:103], v[158:159]
	v_pk_mul_f32 v[154:155], v[100:101], v[154:155]
	v_pk_mul_f32 v[160:161], v[98:99], v[160:161]
	v_pk_mul_f32 v[162:163], v[68:69], v[162:163]
	v_pk_mul_f32 v[168:169], v[66:67], v[168:169]
	v_pk_mul_f32 v[164:165], v[64:65], v[164:165]
	v_pk_mul_f32 v[156:157], v[96:97], v[156:157]
	v_pk_mul_f32 v[166:167], v[70:71], v[166:167]
	v_cvt_pk_bf16_f32 v155, v154, v155
	v_cvt_pk_bf16_f32 v159, v158, v159
	v_cvt_pk_bf16_f32 v161, v160, v161
	v_cvt_pk_bf16_f32 v154, v162, v163
	v_cvt_pk_bf16_f32 v158, v164, v165
	v_cvt_pk_bf16_f32 v160, v168, v169
	v_mov_b32_e32 v162, 0
	v_cvt_pk_bf16_f32 v157, v156, v157
	v_cvt_pk_bf16_f32 v156, v166, v167
	v_mov_b32_dpp v172, v158 row_ror:8 row_mask:0xf bank_mask:0xf
	v_mov_b32_dpp v162, v160 row_ror:8 row_mask:0xf bank_mask:0xf
	v_mov_b32_dpp v171, v156 row_ror:8 row_mask:0xf bank_mask:0xf
	v_cndmask_b32_e64 v156, v157, v172, s[4:5]
	v_cndmask_b32_e64 v160, v172, v157, s[4:5]
	v_cndmask_b32_e64 v157, v161, v162, s[4:5]
	v_cndmask_b32_e64 v161, v162, v161, s[4:5]
	v_or_b32_e32 v162, s1, v144
	v_mov_b32_dpp v170, v154 row_ror:8 row_mask:0xf bank_mask:0xf
	v_lshlrev_b32_e32 v162, 11, v162
	v_cndmask_b32_e64 v154, v155, v170, s[4:5]
	v_cndmask_b32_e64 v158, v170, v155, s[4:5]
	v_cndmask_b32_e64 v155, v159, v171, s[4:5]
	v_add_u32_e32 v163, v152, v162
	v_cndmask_b32_e64 v159, v171, v159, s[4:5]
	global_store_dwordx4 v163, v[154:157], s[12:13] nt
	s_add_i32 s1, s0, 0x80
	v_mov_b32_e32 v170, 0
	v_add_u32_e32 v154, v151, v162
	global_store_dwordx4 v154, v[158:161], s[12:13] nt
	v_or_b32_e32 v154, s1, v140
	s_nop 0
	v_lshl_add_u32 v158, v154, 12, v153
	global_load_dwordx4 v[154:157], v158, s[72:73] nt
	s_nop 0
	global_load_dwordx4 v[158:161], v158, s[72:73] offset:64 nt
	s_waitcnt vmcnt(1)
	v_lshlrev_b32_e32 v162, 16, v154
	v_and_b32_e32 v154, 0xffff0000, v154
	v_lshlrev_b32_e32 v163, 16, v155
	v_lshlrev_b32_e32 v164, 16, v156
	v_and_b32_e32 v156, 0xffff0000, v156
	s_waitcnt vmcnt(0)
	v_lshlrev_b32_e32 v166, 16, v158
	v_and_b32_e32 v158, 0xffff0000, v158
	v_lshlrev_b32_e32 v167, 16, v159
	v_and_b32_e32 v159, 0xffff0000, v159
	v_and_b32_e32 v155, 0xffff0000, v155
	v_lshlrev_b32_e32 v165, 16, v157
	v_and_b32_e32 v157, 0xffff0000, v157
	v_lshlrev_b32_e32 v168, 16, v160
	v_and_b32_e32 v160, 0xffff0000, v160
	v_max_f32_e32 v162, v162, v162
	v_max_f32_e32 v164, v164, v164
	v_max_f32_e32 v171, v154, v154
	v_max_f32_e32 v172, v156, v156
	v_max_f32_e32 v163, v163, v163
	v_max_f32_e32 v166, v166, v166
	v_max_f32_e32 v175, v158, v158
	v_max_f32_e32 v167, v167, v167
	v_max_f32_e32 v177, v159, v159
	v_lshlrev_b32_e32 v169, 16, v161
	v_and_b32_e32 v161, 0xffff0000, v161
	v_max_f32_e32 v165, v165, v165
	v_max_f32_e32 v173, v155, v155
	v_max_f32_e32 v174, v157, v157
	v_max_f32_e32 v168, v168, v168
	v_max_f32_e32 v176, v160, v160
	v_max_f32_e32 v154, 0xda24260, v162
	v_max_f32_e32 v156, 0xda24260, v164
	v_max_f32_e32 v155, 0xda24260, v171
	v_max_f32_e32 v157, 0xda24260, v172
	v_max_f32_e32 v158, 0xda24260, v163
	v_max_f32_e32 v162, 0xda24260, v166
	v_max_f32_e32 v163, 0xda24260, v175
	v_max_f32_e32 v166, 0xda24260, v167
	v_max_f32_e32 v167, 0xda24260, v177
	v_max_f32_e32 v169, v169, v169
	v_max_f32_e32 v178, v161, v161
	v_max_f32_e32 v160, 0xda24260, v165
	v_max_f32_e32 v159, 0xda24260, v173
	v_max_f32_e32 v164, 0xda24260, v168
	v_max_f32_e32 v165, 0xda24260, v176
	v_pk_mul_f32 v[154:155], v[60:61], v[154:155]
	v_pk_mul_f32 v[156:157], v[56:57], v[156:157]
	v_pk_mul_f32 v[166:167], v[30:31], v[166:167]
	v_pk_mul_f32 v[162:163], v[28:29], v[162:163]
	v_max_f32_e32 v161, 0xda24260, v174
	v_max_f32_e32 v168, 0xda24260, v169
	v_max_f32_e32 v169, 0xda24260, v178
	v_pk_mul_f32 v[158:159], v[62:63], v[158:159]
	v_pk_mul_f32 v[164:165], v[24:25], v[164:165]
	v_cvt_pk_bf16_f32 v155, v154, v155
	v_cvt_pk_bf16_f32 v157, v156, v157
	v_cvt_pk_bf16_f32 v154, v162, v163
	v_cvt_pk_bf16_f32 v156, v166, v167
	v_mov_b32_e32 v162, 0
	v_pk_mul_f32 v[160:161], v[58:59], v[160:161]
	v_pk_mul_f32 v[168:169], v[26:27], v[168:169]
	v_cvt_pk_bf16_f32 v159, v158, v159
	v_cvt_pk_bf16_f32 v158, v164, v165
	v_mov_b32_dpp v170, v154 row_ror:8 row_mask:0xf bank_mask:0xf
	v_mov_b32_dpp v162, v156 row_ror:8 row_mask:0xf bank_mask:0xf
	v_mov_b32_e32 v163, 0
	v_cvt_pk_bf16_f32 v161, v160, v161
	v_cvt_pk_bf16_f32 v160, v168, v169
	v_mov_b32_dpp v163, v158 row_ror:8 row_mask:0xf bank_mask:0xf
	v_mov_b32_e32 v164, 0
	v_cndmask_b32_e64 v154, v155, v170, s[4:5]
	v_cndmask_b32_e64 v158, v170, v155, s[4:5]
	v_cndmask_b32_e64 v155, v159, v162, s[4:5]
	v_cndmask_b32_e64 v159, v162, v159, s[4:5]
	v_or_b32_e32 v162, s1, v144
	v_mov_b32_dpp v164, v160 row_ror:8 row_mask:0xf bank_mask:0xf
	v_lshlrev_b32_e32 v162, 11, v162
	v_cndmask_b32_e64 v156, v157, v163, s[4:5]
	v_cndmask_b32_e64 v160, v163, v157, s[4:5]
	v_cndmask_b32_e64 v157, v161, v164, s[4:5]
	v_add_u32_e32 v163, v152, v162
	v_cndmask_b32_e64 v161, v164, v161, s[4:5]
	global_store_dwordx4 v163, v[154:157], s[12:13] nt
	s_add_i32 s1, s0, 0x90
	s_nop 0
	v_add_u32_e32 v154, v151, v162
	global_store_dwordx4 v154, v[158:161], s[12:13] nt
	v_or_b32_e32 v154, s1, v140
	s_nop 0
	v_lshl_add_u32 v158, v154, 12, v153
	global_load_dwordx4 v[154:157], v158, s[72:73] nt
	s_nop 0
	global_load_dwordx4 v[158:161], v158, s[72:73] offset:64 nt
	s_waitcnt vmcnt(1)
; template <class T> DI T gld_nt(const void* base, unsigned off) { return __builtin_nontemporal_load((const T*)((const char*)base + off)); }
; DI u32x4 pk8(const f32x4& a, const f32x4& b) { u32x4 w; w.x = pk2(a[0], a[1]); w.y = pk2(a[2], a[3]); w.z = pk2(b[0], b[1]); w.w = pk2(b[2], b[3]); return w; }
; DI void unpk8(const u32x4& w, f32x4& a, f32x4& b) { a[0] = bf_lo(w.x); a[1] = bf_hi(w.x); a[2] = bf_lo(w.y); a[3] = bf_hi(w.y); b[0] = bf_lo(w.z); b[1] = bf_hi(w.z); b[2] = bf_lo(w.w); b[3] = bf_hi(w.w); }
; template <bool NT = false> DI void st_rows16(void* base, unsigned pitch_b, unsigned row0, unsigned col0, int fr, int fq, const u32x4& w0, const u32x4& w1) {
;   u32x4 x;
; #pragma unroll
;   for (int e = 0; e < 4; ++e) x[e] = (unsigned)__builtin_amdgcn_update_dpp(0, (int)w1[e], 0x128  , 0xf, 0xf, false);
;   const bool hi = fr >= 8;
;   u32x4 pa, pb;
; #pragma unroll
;   for (int e = 0; e < 4; ++e) { pa[e] = hi ? x[e] : w0[e]; pb[e] = hi ? w0[e] : x[e]; }
;   const unsigned ra = row0 + (unsigned)(fr & 7), ca = col0 + 8u * fq + (hi ? 32u : 0u), cb = col0 + 8u * fq + (hi ? 0u : 32u);
;   if (NT) { __builtin_nontemporal_store(pa, (u32x4*)((char*)base + (ra * pitch_b + ca * 2u))); __builtin_nontemporal_store(pb, (u32x4*)((char*)base + ((ra + 8u) * pitch_b + cb * 2u))); }
;   else { gst<u32x4>(base, ra * pitch_b + ca * 2u, pa); gst<u32x4>(base, (ra + 8u) * pitch_b + cb * 2u, pb); }
; }
;   DI void operator()(g8::Acc& acc, int pm, int pn, int wr, int wc, int fr, int fq) const {
;     using namespace g8;
; #pragma unroll
;     for (int ai = 0; ai < 2; ++ai)
; #pragma unroll
;       for (int m = 0; m < 4; ++m) {
;         const int row0 = pm * BM + ai * HALF + wr * 64 + m * 16, row = row0 + fr; u32x4 wv[2];
; #pragma unroll
;         for (int bj = 0; bj < 2; ++bj) {
;           const int col8 = pn * BM + wc * 64 + bj * 32 + fq * 8; const unsigned go = ((unsigned)row * 2048u + (unsigned)(1024 + col8)) * 2u;
;           f32x4 s0, s1; unpk8(gld_nt<u32x4>(gates, go), s0, s1);
; #pragma unroll
;           for (int e = 0; e < 4; ++e) { s0[e] = fmaxf(s0[e], 1e-30f); s1[e] = fmaxf(s1[e], 1e-30f); }
;           wv[bj] = pk8(acc[ai][bj][m][0] * s0, acc[ai][bj][m][1] * s1);
;         }
;         st_rows16(dst, DM * 2u, (unsigned)row0, (unsigned)(pn * BM + wc * 64), fr, fq, wv[0], wv[1]);
;       }
;   }
	v_lshlrev_b32_e32 v162, 16, v154
	v_and_b32_e32 v154, 0xffff0000, v154
	v_lshlrev_b32_e32 v163, 16, v155
	s_waitcnt vmcnt(0)
	v_lshlrev_b32_e32 v166, 16, v158
	v_and_b32_e32 v158, 0xffff0000, v158
	v_and_b32_e32 v155, 0xffff0000, v155
	v_lshlrev_b32_e32 v164, 16, v156
	v_lshlrev_b32_e32 v165, 16, v157
	v_lshlrev_b32_e32 v168, 16, v160
	v_and_b32_e32 v160, 0xffff0000, v160
	v_max_f32_e32 v162, v162, v162
	v_max_f32_e32 v170, v154, v154
	v_max_f32_e32 v163, v163, v163
	v_max_f32_e32 v166, v166, v166
	v_max_f32_e32 v174, v158, v158
	v_and_b32_e32 v156, 0xffff0000, v156
	v_and_b32_e32 v157, 0xffff0000, v157
	v_lshlrev_b32_e32 v167, 16, v159
	v_and_b32_e32 v159, 0xffff0000, v159
	v_lshlrev_b32_e32 v169, 16, v161
	v_and_b32_e32 v161, 0xffff0000, v161
	v_max_f32_e32 v164, v164, v164
	v_max_f32_e32 v165, v165, v165
	v_max_f32_e32 v172, v155, v155
	v_max_f32_e32 v168, v168, v168
	v_max_f32_e32 v175, v160, v160
	v_max_f32_e32 v154, 0xda24260, v162
	v_max_f32_e32 v155, 0xda24260, v170
	v_max_f32_e32 v158, 0xda24260, v163
	v_max_f32_e32 v162, 0xda24260, v166
	v_max_f32_e32 v163, 0xda24260, v174
	v_max_f32_e32 v171, v156, v156
	v_max_f32_e32 v173, v157, v157
	v_max_f32_e32 v167, v167, v167
	v_max_f32_e32 v169, v169, v169
	v_max_f32_e32 v176, v159, v159
	v_max_f32_e32 v177, v161, v161
	v_max_f32_e32 v156, 0xda24260, v164
	v_max_f32_e32 v160, 0xda24260, v165
	v_max_f32_e32 v159, 0xda24260, v172
	v_max_f32_e32 v164, 0xda24260, v168
	v_max_f32_e32 v165, 0xda24260, v175
	v_pk_mul_f32 v[154:155], v[52:53], v[154:155]
	v_pk_mul_f32 v[162:163], v[20:21], v[162:163]
	v_max_f32_e32 v157, 0xda24260, v171
	v_max_f32_e32 v161, 0xda24260, v173
	v_max_f32_e32 v166, 0xda24260, v167
	v_max_f32_e32 v168, 0xda24260, v169
	v_max_f32_e32 v167, 0xda24260, v176
	v_max_f32_e32 v169, 0xda24260, v177
	v_pk_mul_f32 v[158:159], v[54:55], v[158:159]
	v_pk_mul_f32 v[164:165], v[16:17], v[164:165]
	v_cvt_pk_bf16_f32 v155, v154, v155
	v_cvt_pk_bf16_f32 v154, v162, v163
	v_mov_b32_e32 v162, 0
	v_pk_mul_f32 v[160:161], v[50:51], v[160:161]
	v_pk_mul_f32 v[156:157], v[48:49], v[156:157]
	v_pk_mul_f32 v[166:167], v[22:23], v[166:167]
	v_pk_mul_f32 v[168:169], v[18:19], v[168:169]
	v_cvt_pk_bf16_f32 v159, v158, v159
	v_cvt_pk_bf16_f32 v158, v164, v165
	v_mov_b32_dpp v162, v154 row_ror:8 row_mask:0xf bank_mask:0xf
	v_mov_b32_e32 v164, 0
	v_cvt_pk_bf16_f32 v157, v156, v157
	v_cvt_pk_bf16_f32 v161, v160, v161
	v_cvt_pk_bf16_f32 v156, v166, v167
	v_cvt_pk_bf16_f32 v160, v168, v169
	v_mov_b32_e32 v163, 0
	v_mov_b32_dpp v164, v158 row_ror:8 row_mask:0xf bank_mask:0xf
	v_mov_b32_e32 v165, 0
	v_cndmask_b32_e64 v154, v155, v162, s[4:5]
	v_cndmask_b32_e64 v158, v162, v155, s[4:5]
	v_or_b32_e32 v162, s1, v144
	v_mov_b32_dpp v163, v156 row_ror:8 row_mask:0xf bank_mask:0xf
	v_mov_b32_dpp v165, v160 row_ror:8 row_mask:0xf bank_mask:0xf
	v_lshlrev_b32_e32 v162, 11, v162
	v_cndmask_b32_e64 v155, v159, v163, s[4:5]
	v_cndmask_b32_e64 v159, v163, v159, s[4:5]
	v_cndmask_b32_e64 v156, v157, v164, s[4:5]
	v_cndmask_b32_e64 v160, v164, v157, s[4:5]
	v_cndmask_b32_e64 v157, v161, v165, s[4:5]
	v_add_u32_e32 v163, v152, v162
	v_cndmask_b32_e64 v161, v165, v161, s[4:5]
	global_store_dwordx4 v163, v[154:157], s[12:13] nt
	s_add_i32 s1, s0, 0xa0
	s_addk_i32 s0, 0xb0
	v_add_u32_e32 v154, v151, v162
	global_store_dwordx4 v154, v[158:161], s[12:13] nt
	v_or_b32_e32 v154, s1, v140
	s_nop 0
	v_lshl_add_u32 v158, v154, 12, v153
	global_load_dwordx4 v[154:157], v158, s[72:73] nt
	s_nop 0
	global_load_dwordx4 v[158:161], v158, s[72:73] offset:64 nt
	s_waitcnt vmcnt(1)
	v_lshlrev_b32_e32 v162, 16, v154
	v_and_b32_e32 v154, 0xffff0000, v154
	v_lshlrev_b32_e32 v163, 16, v155
	v_lshlrev_b32_e32 v164, 16, v156
	v_and_b32_e32 v156, 0xffff0000, v156
	v_lshlrev_b32_e32 v165, 16, v157
	v_and_b32_e32 v157, 0xffff0000, v157
	s_waitcnt vmcnt(0)
; template <class T> DI T gld_nt(const void* base, unsigned off) { return __builtin_nontemporal_load((const T*)((const char*)base + off)); }
; DI u32x4 pk8(const f32x4& a, const f32x4& b) { u32x4 w; w.x = pk2(a[0], a[1]); w.y = pk2(a[2], a[3]); w.z = pk2(b[0], b[1]); w.w = pk2(b[2], b[3]); return w; }
; DI void unpk8(const u32x4& w, f32x4& a, f32x4& b) { a[0] = bf_lo(w.x); a[1] = bf_hi(w.x); a[2] = bf_lo(w.y); a[3] = bf_hi(w.y); b[0] = bf_lo(w.z); b[1] = bf_hi(w.z); b[2] = bf_lo(w.w); b[3] = bf_hi(w.w); }
; template <bool NT = false> DI void st_rows16(void* base, unsigned pitch_b, unsigned row0, unsigned col0, int fr, int fq, const u32x4& w0, const u32x4& w1) {
;   u32x4 x;
; #pragma unroll
;   for (int e = 0; e < 4; ++e) x[e] = (unsigned)__builtin_amdgcn_update_dpp(0, (int)w1[e], 0x128  , 0xf, 0xf, false);
;   const bool hi = fr >= 8;
;   u32x4 pa, pb;
; #pragma unroll
;   for (int e = 0; e < 4; ++e) { pa[e] = hi ? x[e] : w0[e]; pb[e] = hi ? w0[e] : x[e]; }
;   const unsigned ra = row0 + (unsigned)(fr & 7), ca = col0 + 8u * fq + (hi ? 32u : 0u), cb = col0 + 8u * fq + (hi ? 0u : 32u);
;   if (NT) { __builtin_nontemporal_store(pa, (u32x4*)((char*)base + (ra * pitch_b + ca * 2u))); __builtin_nontemporal_store(pb, (u32x4*)((char*)base + ((ra + 8u) * pitch_b + cb * 2u))); }
;   else { gst<u32x4>(base, ra * pitch_b + ca * 2u, pa); gst<u32x4>(base, (ra + 8u) * pitch_b + cb * 2u, pb); }
; }
;   DI void operator()(g8::Acc& acc, int pm, int pn, int wr, int wc, int fr, int fq) const {
;     using namespace g8;
; #pragma unroll
;     for (int ai = 0; ai < 2; ++ai)
; #pragma unroll
;       for (int m = 0; m < 4; ++m) {
;         const int row0 = pm * BM + ai * HALF + wr * 64 + m * 16, row = row0 + fr; u32x4 wv[2];
; #pragma unroll
;         for (int bj = 0; bj < 2; ++bj) {
;           const int col8 = pn * BM + wc * 64 + bj * 32 + fq * 8; const unsigned go = ((unsigned)row * 2048u + (unsigned)(1024 + col8)) * 2u;
;           f32x4 s0, s1; unpk8(gld_nt<u32x4>(gates, go), s0, s1);
; #pragma unroll
;           for (int e = 0; e < 4; ++e) { s0[e] = fmaxf(s0[e], 1e-30f); s1[e] = fmaxf(s1[e], 1e-30f); }
;           wv[bj] = pk8(acc[ai][bj][m][0] * s0, acc[ai][bj][m][1] * s1);
;         }
;         st_rows16(dst, DM * 2u, (unsigned)row0, (unsigned)(pn * BM + wc * 64), fr, fq, wv[0], wv[1]);
;       }
;   }
	v_lshlrev_b32_e32 v166, 16, v158
	v_and_b32_e32 v158, 0xffff0000, v158
	v_and_b32_e32 v155, 0xffff0000, v155
	v_lshlrev_b32_e32 v167, 16, v159
	v_and_b32_e32 v159, 0xffff0000, v159
	v_lshlrev_b32_e32 v168, 16, v160
	v_and_b32_e32 v160, 0xffff0000, v160
	v_lshlrev_b32_e32 v169, 16, v161
	v_and_b32_e32 v161, 0xffff0000, v161
	v_max_f32_e32 v162, v162, v162
	v_max_f32_e32 v164, v164, v164
	v_max_f32_e32 v170, v154, v154
	v_max_f32_e32 v171, v156, v156
	v_max_f32_e32 v163, v163, v163
	v_max_f32_e32 v165, v165, v165
	v_max_f32_e32 v173, v157, v157
	v_max_f32_e32 v166, v166, v166
	v_max_f32_e32 v174, v158, v158
	v_max_f32_e32 v172, v155, v155
	v_max_f32_e32 v168, v168, v168
	v_max_f32_e32 v175, v160, v160
	v_max_f32_e32 v167, v167, v167
	v_max_f32_e32 v176, v159, v159
	v_max_f32_e32 v177, v161, v161
	v_max_f32_e32 v154, 0xda24260, v162
	v_max_f32_e32 v156, 0xda24260, v164
	v_max_f32_e32 v155, 0xda24260, v170
	v_max_f32_e32 v157, 0xda24260, v171
	v_max_f32_e32 v158, 0xda24260, v163
	v_max_f32_e32 v160, 0xda24260, v165
	v_max_f32_e32 v161, 0xda24260, v173
	v_max_f32_e32 v162, 0xda24260, v166
	v_max_f32_e32 v163, 0xda24260, v174
	v_max_f32_e32 v169, v169, v169
	v_max_f32_e32 v159, 0xda24260, v172
	v_max_f32_e32 v164, 0xda24260, v168
	v_max_f32_e32 v165, 0xda24260, v175
	v_max_f32_e32 v166, 0xda24260, v167
	v_max_f32_e32 v167, 0xda24260, v176
	v_pk_mul_f32 v[154:155], v[44:45], v[154:155]
	v_pk_mul_f32 v[160:161], v[42:43], v[160:161]
	v_pk_mul_f32 v[156:157], v[40:41], v[156:157]
	v_pk_mul_f32 v[162:163], v[12:13], v[162:163]
	v_max_f32_e32 v168, 0xda24260, v169
	v_max_f32_e32 v169, 0xda24260, v177
	v_pk_mul_f32 v[158:159], v[46:47], v[158:159]
	v_pk_mul_f32 v[166:167], v[14:15], v[166:167]
	v_cvt_pk_bf16_f32 v170, v154, v155
	v_cvt_pk_bf16_f32 v157, v156, v157
	v_cvt_pk_bf16_f32 v161, v160, v161
	v_pk_mul_f32 v[154:155], v[8:9], v[164:165]
	v_cvt_pk_bf16_f32 v156, v162, v163
	v_mov_b32_e32 v160, 0
	v_pk_mul_f32 v[168:169], v[10:11], v[168:169]
	v_cvt_pk_bf16_f32 v159, v158, v159
	v_cvt_pk_bf16_f32 v158, v166, v167
	v_cvt_pk_bf16_f32 v154, v154, v155
	v_mov_b32_dpp v160, v156 row_ror:8 row_mask:0xf bank_mask:0xf
	v_mov_b32_e32 v156, 0
	v_mov_b32_e32 v162, 0
	v_cvt_pk_bf16_f32 v155, v168, v169
	v_mov_b32_dpp v156, v158 row_ror:8 row_mask:0xf bank_mask:0xf
	v_mov_b32_dpp v162, v154 row_ror:8 row_mask:0xf bank_mask:0xf
	v_mov_b32_e32 v163, 0
	v_cndmask_b32_e64 v154, v170, v160, s[4:5]
	v_cndmask_b32_e64 v158, v160, v170, s[4:5]
	v_mov_b32_dpp v163, v155 row_ror:8 row_mask:0xf bank_mask:0xf
	v_cndmask_b32_e64 v155, v159, v156, s[4:5]
	v_cndmask_b32_e64 v159, v156, v159, s[4:5]
	v_cndmask_b32_e64 v156, v157, v162, s[4:5]
	v_cndmask_b32_e64 v160, v162, v157, s[4:5]
	v_or_b32_e32 v162, s1, v144
	v_lshlrev_b32_e32 v162, 11, v162
	v_cndmask_b32_e64 v157, v161, v163, s[4:5]
	v_cndmask_b32_e64 v161, v163, v161, s[4:5]
	v_add_u32_e32 v163, v152, v162
	global_store_dwordx4 v163, v[154:157], s[12:13] nt
	s_nop 1
	v_add_u32_e32 v154, v151, v162
	global_store_dwordx4 v154, v[158:161], s[12:13] nt
	v_or_b32_e32 v154, s0, v140
	v_lshl_add_u32 v153, v154, 12, v153
	global_load_dwordx4 v[154:157], v153, s[72:73] nt
	global_load_dwordx4 v[158:161], v153, s[72:73] offset:64 nt
	s_waitcnt vmcnt(1)
	v_lshlrev_b32_e32 v162, 16, v155
	v_and_b32_e32 v155, 0xffff0000, v155
	v_lshlrev_b32_e32 v163, 16, v156
	v_and_b32_e32 v156, 0xffff0000, v156
	v_lshlrev_b32_e32 v153, 16, v154
	v_and_b32_e32 v154, 0xffff0000, v154
	v_lshlrev_b32_e32 v164, 16, v157
	v_and_b32_e32 v157, 0xffff0000, v157
	s_waitcnt vmcnt(0)
	v_lshlrev_b32_e32 v165, 16, v158
	v_and_b32_e32 v158, 0xffff0000, v158
	v_lshlrev_b32_e32 v166, 16, v159
	v_and_b32_e32 v159, 0xffff0000, v159
	v_lshlrev_b32_e32 v168, 16, v161
	v_and_b32_e32 v161, 0xffff0000, v161
	v_max_f32_e32 v163, v163, v163
	v_max_f32_e32 v170, v156, v156
	v_max_f32_e32 v162, v162, v162
	v_max_f32_e32 v171, v155, v155
	v_lshlrev_b32_e32 v167, 16, v160
	v_max_f32_e32 v153, v153, v153
	v_max_f32_e32 v169, v154, v154
	v_max_f32_e32 v172, v157, v157
	v_max_f32_e32 v165, v165, v165
	v_max_f32_e32 v173, v158, v158
	v_max_f32_e32 v168, v168, v168
	v_max_f32_e32 v175, v159, v159
	v_max_f32_e32 v176, v161, v161
	v_max_f32_e32 v156, 0xda24260, v163
	v_max_f32_e32 v157, 0xda24260, v170
	v_max_f32_e32 v158, 0xda24260, v162
	v_max_f32_e32 v159, 0xda24260, v171
	v_and_b32_e32 v160, 0xffff0000, v160
	v_max_f32_e32 v164, v164, v164
	v_max_f32_e32 v167, v167, v167
	v_max_f32_e32 v166, v166, v166
	v_max_f32_e32 v154, 0xda24260, v153
	v_max_f32_e32 v155, 0xda24260, v169
	v_max_f32_e32 v162, 0xda24260, v165
	v_max_f32_e32 v163, 0xda24260, v173
	v_max_f32_e32 v168, 0xda24260, v168
	v_max_f32_e32 v169, 0xda24260, v176
	v_pk_mul_f32 v[158:159], v[38:39], v[158:159]
	v_pk_mul_f32 v[156:157], v[32:33], v[156:157]
	v_max_f32_e32 v174, v160, v160
	v_max_f32_e32 v160, 0xda24260, v164
	v_max_f32_e32 v161, 0xda24260, v172
	v_max_f32_e32 v164, 0xda24260, v167
	v_max_f32_e32 v166, 0xda24260, v166
	v_max_f32_e32 v167, 0xda24260, v175
	v_pk_mul_f32 v[154:155], v[36:37], v[154:155]
	v_cvt_pk_bf16_f32 v170, v158, v159
	v_cvt_pk_bf16_f32 v171, v156, v157
	v_pk_mul_f32 v[156:157], v[4:5], v[162:163]
	v_pk_mul_f32 v[158:159], v[2:3], v[168:169]
	v_max_f32_e32 v165, 0xda24260, v174
	v_pk_mul_f32 v[160:161], v[34:35], v[160:161]
	v_cvt_pk_bf16_f32 v153, v154, v155
	v_pk_mul_f32 v[154:155], v[6:7], v[166:167]
	v_cvt_pk_bf16_f32 v156, v156, v157
	v_cvt_pk_bf16_f32 v157, v158, v159
	v_mov_b32_e32 v158, 0
	v_cvt_pk_bf16_f32 v172, v160, v161
	v_pk_mul_f32 v[160:161], v[0:1], v[164:165]
	v_cvt_pk_bf16_f32 v154, v154, v155
	v_mov_b32_dpp v158, v156 row_ror:8 row_mask:0xf bank_mask:0xf
	v_mov_b32_e32 v156, 0
	v_cvt_pk_bf16_f32 v155, v160, v161
	v_mov_b32_e32 v160, 0
	v_mov_b32_dpp v156, v154 row_ror:8 row_mask:0xf bank_mask:0xf
	v_mov_b32_e32 v161, 0
	v_cndmask_b32_e64 v154, v153, v158, s[4:5]
	v_cndmask_b32_e64 v158, v158, v153, s[4:5]
	v_or_b32_e32 v153, s0, v144
	v_mov_b32_dpp v160, v155 row_ror:8 row_mask:0xf bank_mask:0xf
	v_mov_b32_dpp v161, v157 row_ror:8 row_mask:0xf bank_mask:0xf
	v_lshlrev_b32_e32 v153, 11, v153
	v_cndmask_b32_e64 v155, v170, v156, s[4:5]
	v_cndmask_b32_e64 v159, v156, v170, s[4:5]
	v_cndmask_b32_e64 v156, v171, v160, s[4:5]
	v_cndmask_b32_e64 v160, v160, v171, s[4:5]
	v_cndmask_b32_e64 v157, v172, v161, s[4:5]
	v_cndmask_b32_e64 v161, v161, v172, s[4:5]
	v_add_u32_e32 v152, v152, v153
	v_add_u32_e32 v151, v151, v153
	global_store_dwordx4 v152, v[154:157], s[12:13] nt
	global_store_dwordx4 v151, v[158:161], s[12:13] nt
	s_cbranch_execnz .LBB0_488
